# flat-release grid barrier: XCD leader writes back L2 and bumps global counter; every block polls the global counter directly (no TOPGEN/XGEN hops)
# speedup vs baseline: 1.0246x; 1.0246x over previous
.LBB0_107:
	s_or_b64 exec, exec, s[8:9]
	v_cvt_f32_u32_e32 v4, v2
	s_waitcnt vmcnt(0)
	v_readfirstlane_b32 s3, v3
	v_sub_u32_e32 v3, 0, v2
	v_rcp_iflag_f32_e32 v4, v4
	v_add_u32_e32 v5, s3, v1
	v_mul_f32_e32 v4, 0x4f7ffffe, v4
	v_cvt_u32_f32_e32 v4, v4
	v_mul_lo_u32 v1, v3, v4
	v_mul_hi_u32 v1, v4, v1
	v_add_u32_e32 v1, v4, v1
	v_mul_hi_u32 v1, v5, v1
	v_mul_lo_u32 v3, v1, v2
	v_sub_u32_e32 v3, v5, v3
	v_add_u32_e32 v4, 1, v1
	v_cmp_ge_u32_e32 vcc, v3, v2
	s_nop 1
	v_cndmask_b32_e32 v1, v1, v4, vcc
	v_sub_u32_e32 v4, v3, v2
	v_cndmask_b32_e32 v3, v3, v4, vcc
	v_add_u32_e32 v4, 1, v1
	v_cmp_ge_u32_e32 vcc, v3, v2
	v_add_u32_e32 v3, 1, v5
	s_nop 0
	v_cndmask_b32_e32 v1, v1, v4, vcc
	v_mul_lo_u32 v4, v2, v1
	v_add_u32_e32 v2, v4, v2
	v_cmp_ne_u32_e32 vcc, v3, v2
	s_waitcnt lgkmcnt(0)
	v_add_u32_e32 v4, 1, v1
	v_mul_lo_u32 v4, v4, v0
	s_and_b64 vcc, exec, vcc
	v_mov_b32_e32 v2, 0x3000
	s_cbranch_vccnz .Lxbp_0
	buffer_wbl2 sc1
	s_waitcnt vmcnt(0)
	v_mov_b32_e32 v3, 1
	global_atomic_add v2, v3, s[50:51] offset:1024
.Lxbp_0:
	s_mov_b32 s98, 0
.Lxbs_0:
	global_load_dword v5, v2, s[50:51] offset:1024 sc1
	s_add_i32 s98, s98, 1
	s_waitcnt vmcnt(0)
	v_cmp_ge_u32_e32 vcc, v5, v4
	s_cmp_lt_u32 s98, 0x100000
	s_cbranch_vccnz .Lxbd_0
	s_cbranch_scc0 .Lxbd_0
	s_sleep 1
	s_branch .Lxbs_0
.Lxbd_0:
	buffer_inv sc1
	s_waitcnt vmcnt(0)

.Lxbd_10:
	buffer_inv sc1
	s_waitcnt vmcnt(0)
	v_readlane_b32 s96, v254, 56
	v_readlane_b32 s97, v254, 57
	s_nop 4

.LBB0_1956:
	s_or_b64 exec, exec, s[6:7]
	v_cvt_f32_u32_e32 v4, v2
	s_waitcnt vmcnt(0)
	v_readfirstlane_b32 s4, v3
	v_sub_u32_e32 v3, 0, v2
	v_rcp_iflag_f32_e32 v4, v4
	v_add_u32_e32 v5, s4, v1
	v_mul_f32_e32 v4, 0x4f7ffffe, v4
	v_cvt_u32_f32_e32 v4, v4
	v_mul_lo_u32 v1, v3, v4
	v_mul_hi_u32 v1, v4, v1
	v_add_u32_e32 v1, v4, v1
	v_mul_hi_u32 v1, v5, v1
	v_mul_lo_u32 v3, v1, v2
	v_sub_u32_e32 v3, v5, v3
	v_add_u32_e32 v4, 1, v1
	v_cmp_ge_u32_e32 vcc, v3, v2
	s_nop 1
	v_cndmask_b32_e32 v1, v1, v4, vcc
	v_sub_u32_e32 v4, v3, v2
	v_cndmask_b32_e32 v3, v3, v4, vcc
	v_add_u32_e32 v4, 1, v1
	v_cmp_ge_u32_e32 vcc, v3, v2
	v_add_u32_e32 v3, 1, v5
	s_nop 0
	v_cndmask_b32_e32 v1, v1, v4, vcc
	v_mul_lo_u32 v4, v2, v1
	v_add_u32_e32 v2, v4, v2
	v_cmp_ne_u32_e32 vcc, v3, v2
	s_waitcnt lgkmcnt(0)
	v_add_u32_e32 v4, 1, v1
	v_mul_lo_u32 v4, v4, v0
	s_and_b64 vcc, exec, vcc
	v_mov_b32_e32 v2, 0x3000
	s_cbranch_vccnz .Lxbp_21
	buffer_wbl2 sc1
	s_waitcnt vmcnt(0)
	v_mov_b32_e32 v3, 1
	global_atomic_add v2, v3, s[50:51] offset:1024
